# strategy 4 variant: static s_setprio 1 for the OLDER half (waves 0-3), per-segment flips removed
# baseline (speedup 1.0000x reference)
; #define PG8_STAGE(bufoff, gbase, voff) do { _Pragma("unroll") for (int _i = 0; _i < 2; ++_i) \
;         __builtin_amdgcn_global_load_lds((const unsigned*)((const char*)(gbase) + (voff)[_i]), (LAS unsigned*)(lds + (bufoff) + ldsw + _i * 8192), 16, 0, 0); } while (0)
; #define PG8_BAR __builtin_amdgcn_s_barrier()
; template <class Epi, class Sched>
; __device__ __forceinline__ void gemm_phase(LAS unsigned char* lds, const Gemm g, const Sched& S, const Epi& E) {
;     ...
;     for (int i = 0; i < 2; ++i) { int R, C; stage_rc(tid * 16 + i * 8192, R, C); const int Rb = Epi::PERM ? ((R & ~31) + perm32(R & 31)) : R;
;         voffA[i] = (unsigned)(R * g.lda + C) * 2u; voffB[i] = (unsigned)(Rb * g.ldb + C) * 2u; }
;     const size_t kstep = (size_t)(BK * 2);
;     const size_t hstepA = (size_t)HALF * g.lda * 2, hstepB = (size_t)HALF * g.ldb * 2;
;     const size_t tstepA = 2 * hstepA, tstepB = 2 * hstepB;
;     const unsigned ldsw = (unsigned)wid * 1024u;
;     const int aoff = lds_byte(wr * 64 + fr, fq * 8), boff = lds_byte(wc * 32 + fr, fq * 8);
;     ...
;     Unit cur, nxt; int ui = 0;
;     if (!S.next(0, cur)) return;
;     f32x4 acc[2][2][4][2];
; #pragma unroll
;     for (int a = 0; a < 2; ++a)
; #pragma unroll
;         for (int b = 0; b < 2; ++b)
; #pragma unroll
;             for (int m = 0; m < 4; ++m)
; #pragma unroll
;                 for (int n = 0; n < 2; ++n) acc[a][b][m][n] = (f32x4){0.f, 0.f, 0.f, 0.f};
;     bf16x8 At[4][2], B0[2][2], B1[2][2];
;     const char* cA = (const char*)g.A + (size_t)cur.pm * tstepA + (size_t)cur.ka * 2; const char* cB = (const char*)g.Bt + (size_t)cur.pn * tstepB;
;     S.a_ready(cur);
;     PG8_STAGE(PG8_SB(0, 0), cB, voffB); PG8_STAGE(PG8_SB(0, 1), cB + hstepB, voffB); PG8_STAGE(PG8_SA(0, 0), cA, voffA); PG8_STAGE(PG8_SA(0, 1), cA + hstepA, voffA);
;     if (wr == 1) PG8_BAR;
.LBB0_127:
	s_andn2_b64 vcc, exec, s[10:11]
	v_readlane_b32 s10, v254, 36
	s_or_b32 s65, s64, s10
	s_cbranch_vccnz .LBB0_261
	v_readlane_b32 s12, v253, 6
	s_mov_b64 s[10:11], s[90:91]
	v_mov_b32_e32 v14, v0
	v_readlane_b32 s13, v253, 7
	s_andn2_b64 vcc, exec, s[12:13]
	v_readfirstlane_b32 s16, v14
	s_mul_i32 s67, s65, 0x2b00000
	s_cbranch_vccnz .LBB0_144
	v_lshlrev_b32_e32 v3, 4, v14
	v_add_u32_e32 v2, 0x2000, v3
	v_ashrrev_i32_e32 v4, 31, v2
	v_lshrrev_b32_e32 v4, 22, v4
	v_add_u32_e32 v4, v2, v4
	v_ashrrev_i32_e32 v15, 10, v4
	s_load_dwordx2 s[14:15], s[10:11], 0x98
	v_mul_i32_i24_e32 v4, 0x400, v15
	v_sub_u32_e32 v2, v2, v4
	v_lshrrev_b32_e32 v4, 4, v2
	v_bitop3_b32 v2, v4, v2, 32 bitop3:0x6c
	v_ashrrev_i32_e32 v4, 31, v2
	s_waitcnt lgkmcnt(0)
	s_add_u32 s34, s14, 0x9000000
	v_lshrrev_b32_e32 v4, 26, v4
	s_addc_u32 s42, s15, 0
	v_add_u32_e32 v4, v2, v4
	s_waitcnt vmcnt(0)
	v_lshlrev_b32_e32 v6, 3, v15
	s_add_u32 s10, s14, s67
	v_ashrrev_i32_e32 v16, 6, v4
	v_and_b32_e32 v6, -16, v6
	s_addc_u32 s11, s15, 0
	v_add_u32_e32 v6, v16, v6
	s_add_u32 s43, s10, 0x21400000
	v_and_b32_e32 v7, 3, v16
	s_mov_b32 s10, 0xfffe0
	v_lshrrev_b32_e32 v8, 2, v6
	v_lshlrev_b32_e32 v9, 1, v6
	v_and_b32_e32 v4, 0xc0, v4
	v_and_or_b32 v7, v6, s10, v7
	v_and_b32_e32 v8, 4, v8
	v_and_b32_e32 v9, 24, v9
	v_sub_u32_e32 v2, v2, v4
	v_or3_b32 v7, v7, v8, v9
	v_lshlrev_b32_e32 v8, 5, v15
	v_ashrrev_i16_sdwa v2, v232, sext(v2) dst_sel:DWORD dst_unused:UNUSED_PAD src0_sel:DWORD src1_sel:BYTE_0
	v_and_b32_e32 v8, 32, v8
	v_bfe_i32 v17, v2, 0, 16
	v_add_lshl_u32 v4, v8, v17, 1
	v_lshl_add_u32 v2, v7, 12, v4
	v_lshl_add_u32 v134, v6, 12, v4
	v_bfe_i32 v4, v14, 27, 1
	v_lshrrev_b32_e32 v4, 22, v4
	v_add_u32_e32 v4, v3, v4
	v_and_b32_e32 v4, 0xfffffc00, v4
	v_sub_u32_e32 v3, v3, v4
	v_lshrrev_b32_e32 v4, 4, v3
	v_ashrrev_i32_e32 v6, 31, v14
	v_bitop3_b32 v3, v4, v3, 32 bitop3:0x6c
	v_lshrrev_b32_e32 v6, 26, v6
	v_ashrrev_i32_e32 v4, 31, v3
	v_add_u32_e32 v6, v14, v6
	v_lshrrev_b32_e32 v4, 26, v4
	v_ashrrev_i32_e32 v19, 6, v6
	v_add_u32_e32 v4, v3, v4
	v_lshlrev_b32_e32 v6, 3, v19
	v_ashrrev_i32_e32 v18, 6, v4
	v_and_b32_e32 v6, -16, v6
	s_addc_u32 s44, s11, 0
	s_ashr_i32 s18, s16, 6
	v_add_u32_e32 v6, v18, v6
	v_and_b32_e32 v7, 3, v18
	s_ashr_i32 s17, s16, 8
	s_lshl_b32 s45, s18, 10
	v_and_or_b32 v7, v6, s10, v7
	v_lshrrev_b32_e32 v8, 2, v6
	v_lshlrev_b32_e32 v9, 1, v6
	v_and_b32_e32 v4, 0xc0, v4
	v_readlane_b32 s10, v253, 55
	v_and_b32_e32 v8, 4, v8
	v_and_b32_e32 v9, 24, v9
	v_sub_u32_e32 v3, v3, v4
	v_readlane_b32 s11, v253, 56
	s_add_u32 s26, s34, s10
	v_or3_b32 v7, v7, v8, v9
	v_lshlrev_b32_e32 v8, 5, v19
	v_ashrrev_i16_sdwa v3, v232, sext(v3) dst_sel:DWORD dst_unused:UNUSED_PAD src0_sel:DWORD src1_sel:BYTE_0
	s_addc_u32 s27, s42, s11
	v_readlane_b32 s10, v253, 59
	v_and_b32_e32 v8, 32, v8
	v_bfe_i32 v20, v3, 0, 16
	v_readlane_b32 s11, v253, 60
	s_add_u32 s28, s43, s10
	v_add_lshl_u32 v3, v8, v20, 1
	s_addc_u32 s29, s44, s11
	s_add_i32 s46, s45, 0
	v_lshl_add_u32 v4, v7, 12, v3
	s_add_i32 m0, s46, 0x10000
	v_lshl_add_u32 v136, v6, 12, v3
	global_load_lds_dwordx4 v4, s[28:29]
	s_add_i32 m0, s46, 0x12000
	s_add_u32 s10, s28, 0x80000
	global_load_lds_dwordx4 v2, s[28:29]
	s_addc_u32 s11, s29, 0
	s_add_i32 m0, s46, 0x14000
	s_add_i32 s47, s46, 0x2000
	global_load_lds_dwordx4 v4, s[10:11]
	s_add_i32 m0, s46, 0x16000
	v_mov_b32_e32 v3, v5
	global_load_lds_dwordx4 v2, s[10:11]
	s_mov_b32 m0, s46
	s_add_u32 s10, s26, 0x80000
	global_load_lds_dwordx4 v136, s[26:27]
	s_mov_b32 m0, s47
	s_addc_u32 s11, s27, 0
	s_add_i32 s48, s46, 0x4000
	global_load_lds_dwordx4 v134, s[26:27]
	s_mov_b32 m0, s48
	s_add_i32 s49, s46, 0x6000
	global_load_lds_dwordx4 v136, s[10:11]
	s_mov_b32 m0, s49
	v_mov_b32_e32 v137, v5
	global_load_lds_dwordx4 v134, s[10:11]
	v_mov_b32_e32 v135, v5
	s_cmp_eq_u32 s17, 1
	v_lshl_add_u64 v[12:13], s[28:29], 0, v[4:5]
	v_lshl_add_u64 v[10:11], s[28:29], 0, v[2:3]
	v_lshl_add_u64 v[6:7], s[26:27], 0, v[136:137]
	s_cselect_b64 s[10:11], -1, 0
	s_cmp_lg_u32 s17, 1
	v_lshl_add_u64 v[8:9], s[26:27], 0, v[134:135]
	s_cbranch_scc1 .Lmy_p0_0
	s_barrier
	s_branch .LBB0_131
.Lmy_p0_0:
	s_setprio 1

;     __device__ __forceinline__ void operator()(const f32x4 (&acc)[2][2][4][2], const Unit& u, int wr, int wc, int fr, int fq) const {
;         const int row0 = u.pm * BM + wr * 64 + fr, col0 = u.pn * HALF + wc * 32 + 8 * fq;
;         float rs8[2][4];
;         { f32x4 pa[2][4], pb[2][4];
; #pragma unroll
;           for (int ai = 0; ai < 2; ++ai)
; #pragma unroll
;             for (int m = 0; m < 4; ++m) { const float* p_ = st2 + (size_t)(row0 + ai * HALF + m * 16) * 8; pa[ai][m] = *(const f32x4*)p_; pb[ai][m] = *(const f32x4*)(p_ + 4); }
;           __builtin_amdgcn_sched_barrier(0);
; #pragma unroll
;           for (int ai = 0; ai < 2; ++ai)
; #pragma unroll
;             for (int m = 0; m < 4; ++m) { const f32x4 t_ = pa[ai][m] + pb[ai][m]; rs8[ai][m] = __builtin_amdgcn_rsqf(((t_[0] + t_[1]) + (t_[2] + t_[3])) * (1.0f / (float)D) + 1e-6f); }
;           __builtin_amdgcn_sched_barrier(0); }
.Lmy_rsfill_done:
	s_or_b64 exec, exec, s[100:101]
	s_mov_b32 s100, s54
	s_waitcnt lgkmcnt(0)
	s_barrier
	v_readlane_b32 s19, v253, 54
	s_branch .LBB0_134
	s_nop 0
	s_nop 0
	s_nop 0
	s_nop 0
	s_nop 0
	s_nop 0
	s_nop 0
	s_nop 0
	s_nop 0
	s_nop 0
	s_nop 0
	s_nop 0
	s_nop 0
	s_nop 0
	s_nop 0
	s_nop 0
	s_nop 0
	s_nop 0
	s_nop 0
	s_nop 0
	s_nop 0
	s_nop 0
	s_nop 0
	s_nop 0
	s_nop 0
	s_nop 0
	s_nop 0
	s_nop 0
	s_nop 0
	s_nop 0
	s_nop 0
	s_nop 0
.LBB0_132:
	s_mov_b64 s[26:27], 0

; #define PG8_STAGE(bufoff, gbase, voff) do { _Pragma("unroll") for (int _i = 0; _i < 2; ++_i) \
;         __builtin_amdgcn_global_load_lds((const unsigned*)((const char*)(gbase) + (voff)[_i]), (LAS unsigned*)(lds + (bufoff) + ldsw + _i * 8192), 16, 0, 0); } while (0)
; #define PG8_BAR __builtin_amdgcn_s_barrier()
; template <class Epi, class Sched>
; __device__ __forceinline__ void gemm_phase(LAS unsigned char* lds, const Gemm g, const Sched& S, const Epi& E) {
;     ...
;     for (int i = 0; i < 2; ++i) { int R, C; stage_rc(tid * 16 + i * 8192, R, C); const int Rb = Epi::PERM ? ((R & ~31) + perm32(R & 31)) : R;
;         voffA[i] = (unsigned)(R * g.lda + C) * 2u; voffB[i] = (unsigned)(Rb * g.ldb + C) * 2u; }
;     const size_t kstep = (size_t)(BK * 2);
;     const size_t hstepA = (size_t)HALF * g.lda * 2, hstepB = (size_t)HALF * g.ldb * 2;
;     const size_t tstepA = 2 * hstepA, tstepB = 2 * hstepB;
;     const unsigned ldsw = (unsigned)wid * 1024u;
;     const int aoff = lds_byte(wr * 64 + fr, fq * 8), boff = lds_byte(wc * 32 + fr, fq * 8);
;     ...
;     Unit cur, nxt; int ui = 0;
;     if (!S.next(0, cur)) return;
;     f32x4 acc[2][2][4][2];
; #pragma unroll
;     for (int a = 0; a < 2; ++a)
; #pragma unroll
;         for (int b = 0; b < 2; ++b)
; #pragma unroll
;             for (int m = 0; m < 4; ++m)
; #pragma unroll
;                 for (int n = 0; n < 2; ++n) acc[a][b][m][n] = (f32x4){0.f, 0.f, 0.f, 0.f};
;     bf16x8 At[4][2], B0[2][2], B1[2][2];
;     const char* cA = (const char*)g.A + (size_t)cur.pm * tstepA + (size_t)cur.ka * 2; const char* cB = (const char*)g.Bt + (size_t)cur.pn * tstepB;
;     S.a_ready(cur);
;     PG8_STAGE(PG8_SB(0, 0), cB, voffB); PG8_STAGE(PG8_SB(0, 1), cB + hstepB, voffB); PG8_STAGE(PG8_SA(0, 0), cA, voffA); PG8_STAGE(PG8_SA(0, 1), cA + hstepA, voffA);
;     if (wr == 1) PG8_BAR;
.LBB0_264:
	v_readlane_b32 s12, v253, 41
	v_mov_b32_e32 v143, v0
	v_readlane_b32 s13, v253, 42
	s_andn2_b64 vcc, exec, s[12:13]
	v_readfirstlane_b32 s45, v143
	s_cbranch_vccnz .LBB0_424
	v_lshlrev_b32_e32 v3, 4, v143
	v_add_u32_e32 v2, 0x2000, v3
	v_ashrrev_i32_e32 v4, 31, v2
	v_lshrrev_b32_e32 v4, 22, v4
	v_add_u32_e32 v4, v2, v4
	s_waitcnt vmcnt(0)
	v_ashrrev_i32_e32 v6, 10, v4
	v_mul_i32_i24_e32 v4, 0x400, v6
	v_sub_u32_e32 v2, v2, v4
	v_lshrrev_b32_e32 v4, 4, v2
	v_bitop3_b32 v2, v4, v2, 32 bitop3:0x6c
	v_ashrrev_i32_e32 v4, 31, v2
	v_lshrrev_b32_e32 v4, 26, v4
	s_load_dwordx2 s[12:13], s[10:11], 0x98
	s_load_dwordx2 s[14:15], s[4:5], 0x0
	v_add_u32_e32 v4, v2, v4
	v_ashrrev_i32_e32 v7, 6, v4
	v_and_b32_e32 v4, 0xc0, v4
	s_ashr_i32 s44, s45, 6
	v_sub_u32_e32 v2, v2, v4
	v_bfe_i32 v4, v143, 27, 1
	s_ashr_i32 s47, s45, 8
	s_lshl_b32 s11, s44, 10
	v_lshrrev_b32_e32 v4, 22, v4
	s_waitcnt lgkmcnt(0)
	s_add_u32 s34, s12, 0xd000000
	v_add_u32_e32 v4, v3, v4
	s_addc_u32 s42, s13, 0
	s_mul_i32 s65, s65, 0x1580000
	v_and_b32_e32 v4, 0xfffffc00, v4
	s_add_u32 s4, s12, s65
	v_lshlrev_b32_e32 v8, 3, v6
	v_sub_u32_e32 v3, v3, v4
	s_addc_u32 s5, s13, 0
	v_and_b32_e32 v8, 0x1fffff0, v8
	v_lshrrev_b32_e32 v4, 4, v3
	s_waitcnt vmcnt(4)
	v_ashrrev_i32_e32 v11, 31, v143
	s_add_u32 s43, s4, 0x36c00000
	v_add_u32_e32 v8, v7, v8
	s_movk_i32 s4, 0x1580
	v_bitop3_b32 v3, v4, v3, 32 bitop3:0x6c
	v_lshrrev_b32_e32 v11, 26, v11
	v_mul_lo_u32 v9, v8, s4
	v_lshlrev_b32_e32 v8, 5, v6
	v_ashrrev_i32_e32 v4, 31, v3
	v_add_u32_e32 v11, v143, v11
	v_and_b32_e32 v8, 32, v8
	v_ashrrev_i16_sdwa v2, v232, sext(v2) dst_sel:DWORD dst_unused:UNUSED_PAD src0_sel:DWORD src1_sel:BYTE_0
	v_lshrrev_b32_e32 v4, 26, v4
	v_ashrrev_i32_e32 v11, 6, v11
	v_or_b32_e32 v10, v9, v8
	v_bfe_i32 v9, v2, 0, 16
	v_add_u32_e32 v4, v3, v4
	v_lshlrev_b32_e32 v12, 3, v11
	v_add_lshl_u32 v2, v10, v9, 1
	v_ashrrev_i32_e32 v10, 6, v4
	v_and_b32_e32 v12, 0x1fffff0, v12
	s_addc_u32 s49, s5, 0
	v_add_u32_e32 v12, v10, v12
	v_readlane_b32 s5, v253, 61
	v_mul_lo_u32 v13, v12, s4
	s_mul_i32 s4, s5, 0x2b0000
	v_and_b32_e32 v4, 0xc0, v4
	s_add_u32 s20, s34, s4
	s_mul_hi_i32 s4, s5, 0x2b0000
	v_readlane_b32 s5, v254, 13
	v_lshlrev_b32_e32 v12, 5, v11
	v_sub_u32_e32 v3, v3, v4
	s_addc_u32 s21, s42, s4
	s_mul_i32 s4, s5, 0x2b0000
	v_and_b32_e32 v12, 32, v12
	v_ashrrev_i16_sdwa v3, v232, sext(v3) dst_sel:DWORD dst_unused:UNUSED_PAD src0_sel:DWORD src1_sel:BYTE_0
	s_add_u32 s24, s43, s4
	s_mul_hi_i32 s4, s5, 0x2b0000
	v_or_b32_e32 v14, v13, v12
	v_bfe_i32 v13, v3, 0, 16
	s_addc_u32 s25, s49, s4
	s_add_i32 s50, s11, 0
	v_add_lshl_u32 v4, v14, v13, 1
	s_add_i32 m0, s50, 0x10000
	s_nop 0
	global_load_lds_dwordx4 v4, s[24:25]
	s_add_i32 m0, s50, 0x12000
	s_add_u32 s4, s24, 0x158000
	global_load_lds_dwordx4 v2, s[24:25]
	s_addc_u32 s5, s25, 0
	s_add_i32 m0, s50, 0x14000
	s_add_i32 s51, s50, 0x2000
	global_load_lds_dwordx4 v4, s[4:5]
	s_add_i32 m0, s50, 0x16000
	s_nop 0
	global_load_lds_dwordx4 v2, s[4:5]
	s_mov_b32 m0, s50
	s_add_u32 s4, s20, 0x158000
	global_load_lds_dwordx4 v4, s[20:21]
	s_mov_b32 m0, s51
	s_addc_u32 s5, s21, 0
	s_add_i32 s52, s50, 0x4000
	global_load_lds_dwordx4 v2, s[20:21]
	s_mov_b32 m0, s52
	s_add_i32 s53, s50, 0x6000
	global_load_lds_dwordx4 v4, s[4:5]
	s_mov_b32 m0, s53
	s_cmp_eq_u32 s47, 1
	global_load_lds_dwordx4 v2, s[4:5]
	s_cselect_b64 s[16:17], -1, 0
	s_cmp_lg_u32 s47, 1
	s_cbranch_scc1 .Lmy_p0_1
	s_barrier
	s_branch .LBB0_267

; #define PG8_STAGE(bufoff, gbase, voff) do { _Pragma("unroll") for (int _i = 0; _i < 2; ++_i) \
;         __builtin_amdgcn_global_load_lds((const unsigned*)((const char*)(gbase) + (voff)[_i]), (LAS unsigned*)(lds + (bufoff) + ldsw + _i * 8192), 16, 0, 0); } while (0)
; #define PG8_WAIT_V(n) asm volatile("s_waitcnt vmcnt(" #n ")" ::: "memory")
; #define PG8_BAR __builtin_amdgcn_s_barrier()
; template <class Epi, class Sched>
; __device__ __forceinline__ void gemm_phase(LAS unsigned char* lds, const Gemm g, const Sched& S, const Epi& E) {
;     ...
;     f32x4 acc[2][2][4][2];
; #pragma unroll
;     for (int a = 0; a < 2; ++a)
; #pragma unroll
;         for (int b = 0; b < 2; ++b)
; #pragma unroll
;             for (int m = 0; m < 4; ++m)
; #pragma unroll
;                 for (int n = 0; n < 2; ++n) acc[a][b][m][n] = (f32x4){0.f, 0.f, 0.f, 0.f};
;     ...
;     PG8_STAGE(PG8_SB(0, 0), cB, voffB); PG8_STAGE(PG8_SB(0, 1), cB + hstepB, voffB); PG8_STAGE(PG8_SA(0, 0), cA, voffA); PG8_STAGE(PG8_SA(0, 1), cA + hstepA, voffA);
;     if (wr == 1) PG8_BAR;
;     PG8_WAIT_V(2); PG8_BAR;
;     PG8_STAGE(PG8_SB(1, 0), cB + kstep, voffB); PG8_STAGE(PG8_SA(1, 0), cA + kstep, voffA); PG8_STAGE(PG8_SB(1, 1), cB + hstepB + kstep, voffB);
;     PG8_WAIT_V(6); PG8_BAR;
;     for (;;) {
.LBB0_267:
	v_lshl_add_u64 v[14:15], s[24:25], 0, v[4:5]
	v_mov_b32_e32 v3, v5
	v_and_b32_e32 v142, 15, v143
	v_and_b32_e32 v22, 48, v143
	v_lshlrev_b32_e32 v23, 2, v143
	v_lshl_add_u64 v[16:17], s[24:25], 0, v[2:3]
	s_and_b32 s48, s44, 3
	v_lshl_or_b32 v22, v142, 6, v22
	s_lshl_b32 s4, s47, 13
	v_and_b32_e32 v23, 32, v23
	s_add_i32 m0, s50, 0x18000
	v_lshl_add_u64 v[14:15], v[14:15], 0, s[36:37]
	v_lshl_add_u64 v[18:19], s[20:21], 0, v[4:5]
	v_bitop3_b32 v24, v22, s4, v23 bitop3:0xde
	s_lshl_b32 s4, s48, 12
	s_waitcnt vmcnt(2)
	s_barrier
	global_load_lds_dwordx4 v[14:15], off
	v_lshl_add_u64 v[14:15], v[16:17], 0, s[36:37]
	s_add_i32 m0, s50, 0x1a000
	s_add_i32 s54, s50, 0x8000
	s_add_i32 s55, s50, 0xa000
	v_lshl_add_u64 v[20:21], s[20:21], 0, v[2:3]
	v_bitop3_b32 v144, v22, s4, v23 bitop3:0xde
	global_load_lds_dwordx4 v[14:15], off
	v_lshl_add_u64 v[14:15], v[18:19], 0, s[36:37]
	s_mov_b32 m0, s54
	s_add_u32 s4, s24, 0x158080
	global_load_lds_dwordx4 v[14:15], off
	v_lshl_add_u64 v[14:15], v[20:21], 0, s[36:37]
	s_mov_b32 m0, s55
	s_addc_u32 s5, s25, 0
	global_load_lds_dwordx4 v[14:15], off
	s_add_i32 m0, s50, 0x1c000
	v_lshl_add_u64 v[14:15], s[4:5], 0, v[4:5]
	global_load_lds_dwordx4 v[14:15], off
	v_lshl_add_u64 v[14:15], s[4:5], 0, v[2:3]
	s_add_i32 m0, s50, 0x1e000
	s_movk_i32 s10, 0x1580
	global_load_lds_dwordx4 v[14:15], off
	v_lshrrev_b32_e32 v11, 1, v11
	v_mul_lo_u32 v10, v10, s10
	s_mov_b32 s22, 0x15800
	v_mad_u64_u32 v[10:11], s[4:5], v11, s22, v[10:11]
	v_or_b32_e32 v10, v10, v12
	v_add_lshl_u32 v134, v10, v13, 1
	v_lshrrev_b32_e32 v10, 1, v6
	v_mul_lo_u32 v6, v7, s10
	v_mad_u64_u32 v[6:7], s[4:5], v10, s22, v[6:7]
	s_waitcnt vmcnt(6)
	v_or_b32_e32 v6, v6, v8
	s_cmpk_lt_u32 s45, 0x100
	v_add_lshl_u32 v136, v6, v9, 1
	v_mov_b32_e32 v6, 0
	v_readlane_b32 s4, v254, 13
	s_cselect_b64 s[18:19], -1, 0
	v_mov_b32_e32 v135, v5
	v_mov_b32_e32 v137, v5
	s_mov_b32 s59, 0
	v_add_u32_e32 v145, 0, v24
	s_mov_b32 s10, s4
	v_readlane_b32 s46, v253, 61
	v_mov_b32_e32 v7, v6
	v_mov_b32_e32 v8, v6
	v_mov_b32_e32 v9, v6
	v_mov_b32_e32 v10, v6
	v_mov_b32_e32 v11, v6
	v_mov_b32_e32 v12, v6
	v_mov_b32_e32 v13, v6
	v_mov_b32_e32 v14, v6
	v_mov_b32_e32 v15, v6
	v_mov_b32_e32 v16, v6
	v_mov_b32_e32 v17, v6
	v_mov_b32_e32 v18, v6
	v_mov_b32_e32 v19, v6
	v_mov_b32_e32 v20, v6
	v_mov_b32_e32 v21, v6
	v_mov_b32_e32 v22, v6
	v_mov_b32_e32 v23, v6
	v_mov_b32_e32 v24, v6
	v_mov_b32_e32 v25, v6
	v_mov_b32_e32 v30, v6
	v_mov_b32_e32 v31, v6
	v_mov_b32_e32 v32, v6
	v_mov_b32_e32 v33, v6
	v_mov_b32_e32 v38, v6
	v_mov_b32_e32 v39, v6
	v_mov_b32_e32 v40, v6
	v_mov_b32_e32 v41, v6
	v_mov_b32_e32 v46, v6
	v_mov_b32_e32 v47, v6
	v_mov_b32_e32 v48, v6
	v_mov_b32_e32 v49, v6
	v_mov_b32_e32 v26, v6
	v_mov_b32_e32 v27, v6
	v_mov_b32_e32 v28, v6
	v_mov_b32_e32 v29, v6
	v_mov_b32_e32 v34, v6
	v_mov_b32_e32 v35, v6
	v_mov_b32_e32 v36, v6
	v_mov_b32_e32 v37, v6
	v_mov_b32_e32 v42, v6
	v_mov_b32_e32 v43, v6
	v_mov_b32_e32 v44, v6
	v_mov_b32_e32 v45, v6
	v_mov_b32_e32 v50, v6
	v_mov_b32_e32 v51, v6
	v_mov_b32_e32 v52, v6
	v_mov_b32_e32 v53, v6
	v_mov_b32_e32 v54, v6
	v_mov_b32_e32 v55, v6
	v_mov_b32_e32 v56, v6
	v_mov_b32_e32 v57, v6
	v_mov_b32_e32 v58, v6
	v_mov_b32_e32 v59, v6
	v_mov_b32_e32 v60, v6
	v_mov_b32_e32 v61, v6
	v_mov_b32_e32 v62, v6
	v_mov_b32_e32 v63, v6
	v_mov_b32_e32 v64, v6
	v_mov_b32_e32 v65, v6
	v_mov_b32_e32 v66, v6
	v_mov_b32_e32 v67, v6
	v_mov_b32_e32 v68, v6
	v_mov_b32_e32 v69, v6
	v_mov_b32_e32 v70, v6
	v_mov_b32_e32 v71, v6
	v_mov_b32_e32 v72, v6
	v_mov_b32_e32 v73, v6
	v_mov_b32_e32 v74, v6
	v_mov_b32_e32 v75, v6
	v_mov_b32_e32 v76, v6
	v_mov_b32_e32 v77, v6
	v_mov_b32_e32 v78, v6
	v_mov_b32_e32 v79, v6
	v_mov_b32_e32 v80, v6
	v_mov_b32_e32 v81, v6
	v_mov_b32_e32 v82, v6
	v_mov_b32_e32 v83, v6
	v_mov_b32_e32 v84, v6
	v_mov_b32_e32 v85, v6
	v_mov_b32_e32 v86, v6
	v_mov_b32_e32 v87, v6
	v_mov_b32_e32 v88, v6
	v_mov_b32_e32 v89, v6
	v_mov_b32_e32 v94, v6
	v_mov_b32_e32 v95, v6
	v_mov_b32_e32 v96, v6
	v_mov_b32_e32 v97, v6
	v_mov_b32_e32 v102, v6
	v_mov_b32_e32 v103, v6
	v_mov_b32_e32 v104, v6
	v_mov_b32_e32 v105, v6
	v_mov_b32_e32 v114, v6
	v_mov_b32_e32 v115, v6
	v_mov_b32_e32 v116, v6
	v_mov_b32_e32 v117, v6
	v_mov_b32_e32 v90, v6
	v_mov_b32_e32 v91, v6
	v_mov_b32_e32 v92, v6
	v_mov_b32_e32 v93, v6
	v_mov_b32_e32 v98, v6
	v_mov_b32_e32 v99, v6
	v_mov_b32_e32 v100, v6
	v_mov_b32_e32 v101, v6
	v_mov_b32_e32 v106, v6
	v_mov_b32_e32 v107, v6
	v_mov_b32_e32 v108, v6
	v_mov_b32_e32 v109, v6
	v_mov_b32_e32 v110, v6
	v_mov_b32_e32 v111, v6
	v_mov_b32_e32 v112, v6
	v_mov_b32_e32 v113, v6
	v_mov_b32_e32 v118, v6
	v_mov_b32_e32 v119, v6
	v_mov_b32_e32 v120, v6
	v_mov_b32_e32 v121, v6
	v_mov_b32_e32 v122, v6
	v_mov_b32_e32 v123, v6
	v_mov_b32_e32 v124, v6
	v_mov_b32_e32 v125, v6
	v_mov_b32_e32 v126, v6
	v_mov_b32_e32 v127, v6
	v_mov_b32_e32 v128, v6
	v_mov_b32_e32 v129, v6
	v_mov_b32_e32 v130, v6
	v_mov_b32_e32 v131, v6
	v_mov_b32_e32 v132, v6
	v_mov_b32_e32 v133, v6
	s_barrier
	s_branch .LBB0_270
	s_nop 0
	s_nop 0
	s_nop 0
	s_nop 0
	s_nop 0
	s_nop 0
	s_nop 0
	s_nop 0
	s_nop 0
	s_nop 0
	s_nop 0
	s_nop 0
	s_nop 0
	s_nop 0
	s_nop 0
	s_nop 0
	s_nop 0
	s_nop 0
	s_nop 0
	s_nop 0
	s_nop 0
	s_nop 0
	s_nop 0
	s_nop 0
	s_nop 0
	s_nop 0
	s_nop 0
	s_nop 0
	s_nop 0
	s_nop 0
	s_nop 0
	s_nop 0
	s_nop 0
	s_nop 0
	s_nop 0
	s_nop 0
	s_nop 0
	s_nop 0
	s_nop 0
	s_nop 0
	s_nop 0
	s_nop 0
.LBB0_268:
	s_mov_b64 s[22:23], s[24:25]
	s_mov_b64 s[4:5], s[20:21]
	s_mov_b32 s58, s59
	s_andn2_b64 vcc, exec, s[38:39]
	s_cbranch_vccz .LBB0_288

; #define PG8_STAGE(bufoff, gbase, voff) do { _Pragma("unroll") for (int _i = 0; _i < 2; ++_i) \
;         __builtin_amdgcn_global_load_lds((const unsigned*)((const char*)(gbase) + (voff)[_i]), (LAS unsigned*)(lds + (bufoff) + ldsw + _i * 8192), 16, 0, 0); } while (0)
; #define PG8_BAR __builtin_amdgcn_s_barrier()
; template <class Epi, class Sched>
; __device__ __forceinline__ void gemm_phase(LAS unsigned char* lds, const Gemm g, const Sched& S, const Epi& E) {
;     ...
;     for (int i = 0; i < 2; ++i) { int R, C; stage_rc(tid * 16 + i * 8192, R, C); const int Rb = Epi::PERM ? ((R & ~31) + perm32(R & 31)) : R;
;         voffA[i] = (unsigned)(R * g.lda + C) * 2u; voffB[i] = (unsigned)(Rb * g.ldb + C) * 2u; }
;     const size_t kstep = (size_t)(BK * 2);
;     const size_t hstepA = (size_t)HALF * g.lda * 2, hstepB = (size_t)HALF * g.ldb * 2;
;     const size_t tstepA = 2 * hstepA, tstepB = 2 * hstepB;
;     const unsigned ldsw = (unsigned)wid * 1024u;
;     const int aoff = lds_byte(wr * 64 + fr, fq * 8), boff = lds_byte(wc * 32 + fr, fq * 8);
;     ...
;     Unit cur, nxt; int ui = 0;
;     if (!S.next(0, cur)) return;
;     f32x4 acc[2][2][4][2];
; #pragma unroll
;     for (int a = 0; a < 2; ++a)
; #pragma unroll
;         for (int b = 0; b < 2; ++b)
; #pragma unroll
;             for (int m = 0; m < 4; ++m)
; #pragma unroll
;                 for (int n = 0; n < 2; ++n) acc[a][b][m][n] = (f32x4){0.f, 0.f, 0.f, 0.f};
;     bf16x8 At[4][2], B0[2][2], B1[2][2];
;     const char* cA = (const char*)g.A + (size_t)cur.pm * tstepA + (size_t)cur.ka * 2; const char* cB = (const char*)g.Bt + (size_t)cur.pn * tstepB;
;     S.a_ready(cur);
;     PG8_STAGE(PG8_SB(0, 0), cB, voffB); PG8_STAGE(PG8_SB(0, 1), cB + hstepB, voffB); PG8_STAGE(PG8_SA(0, 0), cA, voffA); PG8_STAGE(PG8_SA(0, 1), cA + hstepA, voffA);
;     if (wr == 1) PG8_BAR;
.LBB0_504:
	s_load_dwordx2 s[8:9], s[6:7], 0x98
	s_load_dwordx2 s[14:15], s[6:7], 0x70
	s_waitcnt lgkmcnt(0)
	s_add_u32 s47, s8, 0x9000000
	s_addc_u32 s48, s9, 0
	s_add_u32 s34, s8, 0x45c00000
	s_addc_u32 s46, s9, 0
	s_add_u32 s6, s8, 0xd000000
	s_addc_u32 s7, s9, 0
	s_add_u32 s12, s8, 0xa00000
	s_addc_u32 s13, s9, 0
	s_add_u32 s10, s8, 0xb00000
	s_addc_u32 s11, s9, 0
	s_add_u32 s8, s8, 0x100000
	s_addc_u32 s9, s9, 0
	s_and_b64 vcc, exec, s[4:5]
	s_cbranch_vccnz .LBB0_538
	v_ashrrev_i32_e32 v2, 31, v4
	v_lshrrev_b32_e32 v2, 26, v2
	v_add_u32_e32 v2, v4, v2
	v_ashrrev_i32_e32 v14, 6, v2
	v_bfe_i32 v2, v4, 27, 1
	v_lshlrev_b32_e32 v3, 4, v4
	v_lshrrev_b32_e32 v2, 22, v2
	v_add_u32_e32 v2, v3, v2
	v_and_b32_e32 v2, 0xfffffc00, v2
	v_sub_u32_e32 v2, v3, v2
	s_waitcnt vmcnt(0)
	v_lshrrev_b32_e32 v6, 4, v2
	v_bitop3_b32 v2, v6, v2, 32 bitop3:0x6c
	v_ashrrev_i32_e32 v7, 31, v2
	v_lshrrev_b32_e32 v7, 26, v7
	v_add_u32_e32 v7, v2, v7
	v_lshlrev_b32_e32 v6, 3, v14
	v_ashrrev_i32_e32 v15, 6, v7
	v_and_b32_e32 v7, 0xc0, v7
	v_and_b32_e32 v6, -16, v6
	v_sub_u32_e32 v2, v2, v7
	v_add_u32_e32 v6, v15, v6
	v_lshlrev_b32_e32 v8, 5, v14
	v_ashrrev_i16_sdwa v2, v232, sext(v2) dst_sel:DWORD dst_unused:UNUSED_PAD src0_sel:DWORD src1_sel:BYTE_0
	v_and_b32_e32 v8, 32, v8
	v_bfe_i32 v16, v2, 0, 16
	v_lshlrev_b32_e32 v2, 1, v6
	v_lshrrev_b32_e32 v7, 2, v6
	v_and_b32_e32 v9, 3, v15
	s_mov_b32 s4, 0xfffe0
	v_and_b32_e32 v2, 24, v2
	v_and_b32_e32 v7, 4, v7
	v_and_or_b32 v9, v6, s4, v9
	v_add_lshl_u32 v8, v8, v16, 1
	v_add_u32_e32 v3, 0x2000, v3
	v_or3_b32 v7, v9, v7, v2
	v_lshl_add_u32 v2, v6, 12, v8
	v_ashrrev_i32_e32 v6, 31, v3
	v_lshrrev_b32_e32 v6, 22, v6
	v_add_u32_e32 v6, v3, v6
	v_ashrrev_i32_e32 v17, 10, v6
	v_mul_i32_i24_e32 v6, 0x400, v17
	v_sub_u32_e32 v3, v3, v6
	v_lshrrev_b32_e32 v6, 4, v3
	v_bitop3_b32 v3, v6, v3, 32 bitop3:0x6c
	v_lshl_add_u32 v212, v7, 12, v8
	v_ashrrev_i32_e32 v7, 31, v3
	v_lshrrev_b32_e32 v7, 26, v7
	v_lshlrev_b32_e32 v6, 3, v17
	v_add_u32_e32 v7, v3, v7
	v_and_b32_e32 v6, -16, v6
	v_ashrrev_i32_e32 v18, 6, v7
	s_ashr_i32 s17, s16, 6
	v_add_u32_e32 v6, v18, v6
	v_and_b32_e32 v9, 3, v18
	s_ashr_i32 s29, s28, 31
	v_and_or_b32 v9, v6, s4, v9
	s_ashr_i32 s18, s16, 8
	s_lshl_b32 s49, s17, 10
	s_lshl_b64 s[4:5], s[28:29], 20
	s_add_u32 s38, s47, s4
	v_and_b32_e32 v7, 0xc0, v7
	s_addc_u32 s39, s48, s5
	s_ashr_i32 s27, s26, 31
	v_sub_u32_e32 v3, v3, v7
	s_lshl_b64 s[4:5], s[26:27], 20
	v_ashrrev_i16_sdwa v3, v232, sext(v3) dst_sel:DWORD dst_unused:UNUSED_PAD src0_sel:DWORD src1_sel:BYTE_0
	s_add_u32 s42, s34, s4
	v_lshlrev_b32_e32 v8, 5, v17
	v_bfe_i32 v19, v3, 0, 16
	v_lshlrev_b32_e32 v3, 1, v6
	v_lshrrev_b32_e32 v7, 2, v6
	s_addc_u32 s43, s46, s5
	s_add_i32 s50, s49, 0
	v_and_b32_e32 v8, 32, v8
	v_and_b32_e32 v3, 24, v3
	v_and_b32_e32 v7, 4, v7
	s_add_i32 m0, s50, 0x10000
	v_or3_b32 v3, v9, v7, v3
	v_add_lshl_u32 v7, v8, v19, 1
	global_load_lds_dwordx4 v212, s[42:43]
	s_add_i32 m0, s50, 0x12000
	v_lshl_add_u32 v216, v3, 12, v7
	s_add_u32 s4, s42, 0x80000
	global_load_lds_dwordx4 v216, s[42:43]
	s_addc_u32 s5, s43, 0
	s_add_i32 m0, s50, 0x14000
	s_add_i32 s51, s50, 0x2000
	global_load_lds_dwordx4 v212, s[4:5]
	s_add_i32 m0, s50, 0x16000
	v_lshl_add_u32 v214, v6, 12, v7
	global_load_lds_dwordx4 v216, s[4:5]
	s_mov_b32 m0, s50
	s_add_u32 s4, s38, 0x80000
	global_load_lds_dwordx4 v2, s[38:39]
	s_mov_b32 m0, s51
	s_addc_u32 s5, s39, 0
	s_add_i32 s52, s50, 0x4000
	global_load_lds_dwordx4 v214, s[38:39]
	s_mov_b32 m0, s52
	s_add_i32 s53, s50, 0x6000
	global_load_lds_dwordx4 v2, s[4:5]
	s_mov_b32 m0, s53
	v_mov_b32_e32 v213, v5
	global_load_lds_dwordx4 v214, s[4:5]
	v_mov_b32_e32 v217, v5
	v_mov_b32_e32 v3, v5
	v_mov_b32_e32 v215, v5
	s_cmp_eq_u32 s18, 1
	s_waitcnt vmcnt(0)
	v_lshl_add_u64 v[12:13], s[42:43], 0, v[212:213]
	v_lshl_add_u64 v[10:11], s[42:43], 0, v[216:217]
	v_lshl_add_u64 v[6:7], s[38:39], 0, v[2:3]
	s_cselect_b64 s[4:5], -1, 0
	s_cmp_lg_u32 s18, 1
	v_lshl_add_u64 v[8:9], s[38:39], 0, v[214:215]
	s_cbranch_scc1 .Lmy_p0_2
	s_barrier
	s_branch .LBB0_507

; #define PG8_STAGE(bufoff, gbase, voff) do { _Pragma("unroll") for (int _i = 0; _i < 2; ++_i) \
;         __builtin_amdgcn_global_load_lds((const unsigned*)((const char*)(gbase) + (voff)[_i]), (LAS unsigned*)(lds + (bufoff) + ldsw + _i * 8192), 16, 0, 0); } while (0)
; #define PG8_WAIT_V(n) asm volatile("s_waitcnt vmcnt(" #n ")" ::: "memory")
; #define PG8_BAR __builtin_amdgcn_s_barrier()
;     __device__ __forceinline__ void operator()(const f32x4 (&acc)[2][2][4][2], const Unit& u, int wr, int wc, int fr, int fq) const {
;         const int row0 = u.pm * BM + wr * 64 + fr, j0 = 8 * fq, cbase = u.pn * BM + 64 * wc;
;         const f32x4 ba0 = *(const f32x4*)(bias + cbase + j0), ba1 = *(const f32x4*)(bias + cbase + j0 + 4), bb0 = *(const f32x4*)(bias + cbase + 32 + j0), bb1 = *(const f32x4*)(bias + cbase + 32 + j0 + 4);
;         const bool rot = u.pn < 9;
;         f32x4 TB[2][6];
; template <class Epi, class Sched>
; __device__ __forceinline__ void gemm_phase(LAS unsigned char* lds, const Gemm g, const Sched& S, const Epi& E) {
;     ...
;     PG8_WAIT_V(2); PG8_BAR;
;     PG8_STAGE(PG8_SB(1, 0), cB + kstep, voffB); PG8_STAGE(PG8_SA(1, 0), cA + kstep, voffA); PG8_STAGE(PG8_SB(1, 1), cB + hstepB + kstep, voffB);
;     PG8_WAIT_V(6); PG8_BAR;
.LBB0_507:
	v_lshrrev_b32_e32 v20, 1, v4
	v_and_b32_e32 v20, 24, v20
	v_and_b32_e32 v21, 15, v4
	v_lshlrev_b32_e32 v22, 1, v20
	v_lshlrev_b32_e32 v4, 2, v4
	s_and_b32 s20, s17, 3
	v_lshl_or_b32 v235, s18, 6, v21
	v_lshl_or_b32 v21, v21, 6, v22
	s_lshl_b32 s17, s18, 13
	v_and_b32_e32 v4, 32, v4
	s_add_i32 m0, s50, 0x18000
	v_lshl_add_u64 v[12:13], v[12:13], 0, s[36:37]
	v_bitop3_b32 v22, v21, s17, v4 bitop3:0xde
	s_lshl_b32 s17, s20, 12
	s_waitcnt vmcnt(2)
	s_barrier
	global_load_lds_dwordx4 v[12:13], off
	v_lshl_add_u64 v[10:11], v[10:11], 0, s[36:37]
	s_add_i32 m0, s50, 0x1a000
	s_add_i32 s54, s50, 0x8000
	s_add_i32 s55, s50, 0xa000
	global_load_lds_dwordx4 v[10:11], off
	v_lshl_add_u64 v[6:7], v[6:7], 0, s[36:37]
	s_mov_b32 m0, s54
	s_add_u32 s18, s42, 0x80080
	global_load_lds_dwordx4 v[6:7], off
	v_lshl_add_u64 v[6:7], v[8:9], 0, s[36:37]
	s_mov_b32 m0, s55
	s_addc_u32 s19, s43, 0
	global_load_lds_dwordx4 v[6:7], off
	s_add_i32 m0, s50, 0x1c000
	v_lshl_add_u64 v[6:7], s[18:19], 0, v[212:213]
	global_load_lds_dwordx4 v[6:7], off
	v_lshl_add_u64 v[6:7], s[18:19], 0, v[216:217]
	s_add_i32 m0, s50, 0x1e000
	v_bitop3_b32 v236, v21, s17, v4 bitop3:0xde
	global_load_lds_dwordx4 v[6:7], off
	v_lshlrev_b32_e32 v4, 2, v20
	v_lshl_add_u64 v[218:219], s[12:13], 0, v[4:5]
	v_lshl_add_u64 v[220:221], s[10:11], 0, v[4:5]
	v_lshl_add_u64 v[222:223], s[14:15], 0, v[4:5]
	v_lshlrev_b32_e32 v4, 15, v14
	v_and_b32_e32 v4, 0xffff0000, v4
	v_lshl_add_u32 v4, v15, 12, v4
	v_and_b32_e32 v6, 1, v14
	v_lshl_or_b32 v4, v6, 6, v4
	v_lshl_add_u32 v224, v16, 1, v4
	v_lshlrev_b32_e32 v4, 15, v17
	v_and_b32_e32 v4, 0xffff0000, v4
	s_waitcnt vmcnt(6)
	v_lshl_add_u32 v4, v18, 12, v4
	v_and_b32_e32 v6, 1, v17
	s_cmpk_lt_u32 s16, 0x100
	v_lshl_or_b32 v4, v6, 6, v4
	s_cselect_b64 s[16:17], -1, 0
	s_lshl_b32 s56, s20, 6
	v_mov_b32_e32 v225, v5
	v_lshl_add_u32 v226, v19, 1, v4
	v_mov_b32_e32 v227, v5
	s_mov_b32 s57, 0
	v_add_u32_e32 v237, 0, v22
	v_lshlrev_b32_e32 v4, 1, v20
	s_barrier
	s_branch .LBB0_510
	s_nop 0
	s_nop 0
	s_nop 0
	s_nop 0
	s_nop 0
	s_nop 0
	s_nop 0
	s_nop 0
	s_nop 0
	s_nop 0
	s_nop 0
	s_nop 0
	s_nop 0
	s_nop 0
	s_nop 0
.LBB0_508:
	s_mov_b64 s[26:27], 0

; #define PG8_STAGE(bufoff, gbase, voff) do { _Pragma("unroll") for (int _i = 0; _i < 2; ++_i) \
;         __builtin_amdgcn_global_load_lds((const unsigned*)((const char*)(gbase) + (voff)[_i]), (LAS unsigned*)(lds + (bufoff) + ldsw + _i * 8192), 16, 0, 0); } while (0)
; #define PG8_BAR __builtin_amdgcn_s_barrier()
; template <class Epi, class Sched>
; __device__ __forceinline__ void gemm_phase(LAS unsigned char* lds, const Gemm g, const Sched& S, const Epi& E) {
;     ...
;     for (int i = 0; i < 2; ++i) { int R, C; stage_rc(tid * 16 + i * 8192, R, C); const int Rb = Epi::PERM ? ((R & ~31) + perm32(R & 31)) : R;
;         voffA[i] = (unsigned)(R * g.lda + C) * 2u; voffB[i] = (unsigned)(Rb * g.ldb + C) * 2u; }
;     const size_t kstep = (size_t)(BK * 2);
;     const size_t hstepA = (size_t)HALF * g.lda * 2, hstepB = (size_t)HALF * g.ldb * 2;
;     const size_t tstepA = 2 * hstepA, tstepB = 2 * hstepB;
;     const unsigned ldsw = (unsigned)wid * 1024u;
;     const int aoff = lds_byte(wr * 64 + fr, fq * 8), boff = lds_byte(wc * 32 + fr, fq * 8);
;     ...
;     Unit cur, nxt; int ui = 0;
;     if (!S.next(0, cur)) return;
;     f32x4 acc[2][2][4][2];
; #pragma unroll
;     for (int a = 0; a < 2; ++a)
; #pragma unroll
;         for (int b = 0; b < 2; ++b)
; #pragma unroll
;             for (int m = 0; m < 4; ++m)
; #pragma unroll
;                 for (int n = 0; n < 2; ++n) acc[a][b][m][n] = (f32x4){0.f, 0.f, 0.f, 0.f};
;     bf16x8 At[4][2], B0[2][2], B1[2][2];
;     const char* cA = (const char*)g.A + (size_t)cur.pm * tstepA + (size_t)cur.ka * 2; const char* cB = (const char*)g.Bt + (size_t)cur.pn * tstepB;
;     S.a_ready(cur);
;     PG8_STAGE(PG8_SB(0, 0), cB, voffB); PG8_STAGE(PG8_SB(0, 1), cB + hstepB, voffB); PG8_STAGE(PG8_SA(0, 0), cA, voffA); PG8_STAGE(PG8_SA(0, 1), cA + hstepA, voffA);
;     if (wr == 1) PG8_BAR;
.LBB0_646:
	s_and_b64 vcc, exec, s[4:5]
	s_cbranch_vccnz .LBB0_730
	v_ashrrev_i32_e32 v2, 31, v4
	v_lshrrev_b32_e32 v2, 26, v2
	v_add_u32_e32 v2, v4, v2
	v_ashrrev_i32_e32 v14, 6, v2
	v_bfe_i32 v2, v4, 27, 1
	v_lshlrev_b32_e32 v3, 4, v4
	v_lshrrev_b32_e32 v2, 22, v2
	v_add_u32_e32 v2, v3, v2
	v_and_b32_e32 v2, 0xfffffc00, v2
	v_sub_u32_e32 v2, v3, v2
	s_waitcnt vmcnt(0)
	v_lshrrev_b32_e32 v6, 4, v2
	v_bitop3_b32 v2, v6, v2, 32 bitop3:0x6c
	v_ashrrev_i32_e32 v7, 31, v2
	v_lshrrev_b32_e32 v7, 26, v7
	v_add_u32_e32 v7, v2, v7
	v_lshlrev_b32_e32 v6, 3, v14
	v_ashrrev_i32_e32 v15, 6, v7
	v_and_b32_e32 v7, 0xc0, v7
	v_and_b32_e32 v6, -16, v6
	v_sub_u32_e32 v2, v2, v7
	v_add_u32_e32 v6, v15, v6
	v_lshlrev_b32_e32 v8, 5, v14
	v_ashrrev_i16_sdwa v2, v232, sext(v2) dst_sel:DWORD dst_unused:UNUSED_PAD src0_sel:DWORD src1_sel:BYTE_0
	v_and_b32_e32 v8, 32, v8
	v_bfe_i32 v16, v2, 0, 16
	v_lshlrev_b32_e32 v2, 1, v6
	v_lshrrev_b32_e32 v7, 2, v6
	v_and_b32_e32 v9, 3, v15
	s_mov_b32 s4, 0xfffe0
	v_and_b32_e32 v2, 24, v2
	v_and_b32_e32 v7, 4, v7
	v_and_or_b32 v9, v6, s4, v9
	v_add_lshl_u32 v8, v8, v16, 1
	v_add_u32_e32 v3, 0x2000, v3
	v_or3_b32 v7, v9, v7, v2
	v_lshl_add_u32 v2, v6, 12, v8
	v_ashrrev_i32_e32 v6, 31, v3
	v_lshrrev_b32_e32 v6, 22, v6
	v_add_u32_e32 v6, v3, v6
	v_ashrrev_i32_e32 v17, 10, v6
	s_load_dwordx2 s[14:15], s[8:9], 0x98
	v_mul_i32_i24_e32 v6, 0x400, v17
	v_sub_u32_e32 v3, v3, v6
	v_lshrrev_b32_e32 v6, 4, v3
	v_bitop3_b32 v3, v6, v3, 32 bitop3:0x6c
	v_lshl_add_u32 v182, v7, 12, v8
	v_ashrrev_i32_e32 v7, 31, v3
	s_waitcnt lgkmcnt(0)
	s_add_u32 s42, s14, 0x9000000
	v_lshrrev_b32_e32 v7, 26, v7
	s_addc_u32 s43, s15, 0
	v_lshlrev_b32_e32 v6, 3, v17
	v_add_u32_e32 v7, v3, v7
	s_add_u32 s44, s14, 0x41c00000
	v_and_b32_e32 v6, -16, v6
	v_ashrrev_i32_e32 v18, 6, v7
	s_addc_u32 s45, s15, 0
	s_ashr_i32 s13, s12, 6
	v_add_u32_e32 v6, v18, v6
	v_and_b32_e32 v9, 3, v18
	s_ashr_i32 s25, s24, 31
	v_and_or_b32 v9, v6, s4, v9
	s_ashr_i32 s16, s12, 8
	s_lshl_b32 s46, s13, 10
	s_lshl_b64 s[4:5], s[24:25], 20
	s_add_u32 s26, s42, s4
	v_and_b32_e32 v7, 0xc0, v7
	s_addc_u32 s27, s43, s5
	s_ashr_i32 s23, s22, 31
	v_sub_u32_e32 v3, v3, v7
	s_lshl_b64 s[4:5], s[22:23], 20
	v_ashrrev_i16_sdwa v3, v232, sext(v3) dst_sel:DWORD dst_unused:UNUSED_PAD src0_sel:DWORD src1_sel:BYTE_0
	s_add_u32 s28, s44, s4
	v_lshlrev_b32_e32 v8, 5, v17
	v_bfe_i32 v19, v3, 0, 16
	v_lshlrev_b32_e32 v3, 1, v6
	v_lshrrev_b32_e32 v7, 2, v6
	s_addc_u32 s29, s45, s5
	s_add_i32 s47, s46, 0
	v_and_b32_e32 v8, 32, v8
	v_and_b32_e32 v3, 24, v3
	v_and_b32_e32 v7, 4, v7
	s_add_i32 m0, s47, 0x10000
	v_or3_b32 v3, v9, v7, v3
	v_add_lshl_u32 v7, v8, v19, 1
	global_load_lds_dwordx4 v182, s[28:29]
	s_add_i32 m0, s47, 0x12000
	v_lshl_add_u32 v186, v3, 12, v7
	s_add_u32 s4, s28, 0x80000
	global_load_lds_dwordx4 v186, s[28:29]
	s_addc_u32 s5, s29, 0
	s_add_i32 m0, s47, 0x14000
	s_add_i32 s48, s47, 0x2000
	global_load_lds_dwordx4 v182, s[4:5]
	s_add_i32 m0, s47, 0x16000
	v_lshl_add_u32 v184, v6, 12, v7
	global_load_lds_dwordx4 v186, s[4:5]
	s_mov_b32 m0, s47
	s_add_u32 s4, s26, 0x80000
	global_load_lds_dwordx4 v2, s[26:27]
	s_mov_b32 m0, s48
	s_addc_u32 s5, s27, 0
	s_add_i32 s49, s47, 0x4000
	global_load_lds_dwordx4 v184, s[26:27]
	s_mov_b32 m0, s49
	s_add_i32 s50, s47, 0x6000
	global_load_lds_dwordx4 v2, s[4:5]
	s_mov_b32 m0, s50
	v_mov_b32_e32 v183, v5
	global_load_lds_dwordx4 v184, s[4:5]
	v_mov_b32_e32 v187, v5
	v_mov_b32_e32 v3, v5
	v_mov_b32_e32 v185, v5
	s_cmp_eq_u32 s16, 1
	s_waitcnt vmcnt(0)
	v_lshl_add_u64 v[12:13], s[28:29], 0, v[182:183]
	v_lshl_add_u64 v[10:11], s[28:29], 0, v[186:187]
	v_lshl_add_u64 v[6:7], s[26:27], 0, v[2:3]
	s_cselect_b64 s[4:5], -1, 0
	s_cmp_lg_u32 s16, 1
	v_lshl_add_u64 v[8:9], s[26:27], 0, v[184:185]
	s_cbranch_scc1 .Lmy_p0_3
	s_barrier
	s_branch .LBB0_649

; __device__ __forceinline__ float log2_gamma(int hd) { const float e = ldexpf(1.0f, -5 - hd); float p = 1.0f / 7.0f; p = p * e + 1.0f / 6.0f; p = p * e + 0.2f; p = p * e + 0.25f; p = p * e + 1.0f / 3.0f; p = p * e + 0.5f; p = p * e + 1.0f; return -1.44269504089f * e * p; }
; #define PG8_STAGE(bufoff, gbase, voff) do { _Pragma("unroll") for (int _i = 0; _i < 2; ++_i) \
;         __builtin_amdgcn_global_load_lds((const unsigned*)((const char*)(gbase) + (voff)[_i]), (LAS unsigned*)(lds + (bufoff) + ldsw + _i * 8192), 16, 0, 0); } while (0)
; #define PG8_WAIT_V(n) asm volatile("s_waitcnt vmcnt(" #n ")" ::: "memory")
; #define PG8_BAR __builtin_amdgcn_s_barrier()
;     __device__ __forceinline__ void operator()(const f32x4 (&acc)[2][2][4][2], const Unit& u, int wr, int wc, int fr, int fq) const {
;         const int row0 = u.pm * BM + wr * 64 + fr, j0 = wc * 32 + 8 * fq;
;         if (u.pn < 16) {
;             const int hd = u.pn & 7; const bool isq = u.pn < 8;
;             const float l2g = log2_gamma(hd);
;             f32x4 TB[2][6];
; template <class Epi, class Sched>
; __device__ __forceinline__ void gemm_phase(LAS unsigned char* lds, const Gemm g, const Sched& S, const Epi& E) {
;     ...
;     PG8_WAIT_V(2); PG8_BAR;
;     PG8_STAGE(PG8_SB(1, 0), cB + kstep, voffB); PG8_STAGE(PG8_SA(1, 0), cA + kstep, voffA); PG8_STAGE(PG8_SB(1, 1), cB + hstepB + kstep, voffB);
;     PG8_WAIT_V(6); PG8_BAR;
.LBB0_649:
	s_add_u32 s8, s14, 0xd000000
	v_lshrrev_b32_e32 v20, 1, v4
	s_addc_u32 s9, s15, 0
	v_and_b32_e32 v189, 15, v4
	v_and_b32_e32 v21, 24, v20
	s_add_u32 s10, s14, 0x100000
	v_lshlrev_b32_e32 v20, 1, v21
	v_lshlrev_b32_e32 v22, 6, v189
	v_lshlrev_b32_e32 v4, 2, v4
	s_addc_u32 s11, s15, 0
	s_and_b32 s18, s13, 3
	v_or_b32_e32 v23, v22, v20
	s_lshl_b32 s13, s16, 13
	v_and_b32_e32 v4, 32, v4
	s_add_i32 m0, s47, 0x18000
	v_lshl_add_u64 v[12:13], v[12:13], 0, s[36:37]
	s_lshl_b32 s51, s16, 6
	v_bitop3_b32 v24, v23, s13, v4 bitop3:0xde
	s_lshl_b32 s13, s18, 12
	s_waitcnt vmcnt(2)
	s_barrier
	global_load_lds_dwordx4 v[12:13], off
	v_lshl_add_u64 v[10:11], v[10:11], 0, s[36:37]
	s_add_i32 m0, s47, 0x1a000
	s_add_i32 s52, s47, 0x8000
	s_add_i32 s53, s47, 0xa000
	global_load_lds_dwordx4 v[10:11], off
	v_lshl_add_u64 v[6:7], v[6:7], 0, s[36:37]
	s_mov_b32 m0, s52
	s_add_u32 s16, s28, 0x80080
	global_load_lds_dwordx4 v[6:7], off
	v_lshl_add_u64 v[6:7], v[8:9], 0, s[36:37]
	s_mov_b32 m0, s53
	s_addc_u32 s17, s29, 0
	global_load_lds_dwordx4 v[6:7], off
	s_add_i32 m0, s47, 0x1c000
	v_lshl_add_u64 v[6:7], s[16:17], 0, v[182:183]
	global_load_lds_dwordx4 v[6:7], off
	v_lshl_add_u64 v[6:7], s[16:17], 0, v[186:187]
	s_add_i32 m0, s47, 0x1e000
	v_lshl_or_b32 v188, s18, 5, v21
	global_load_lds_dwordx4 v[6:7], off
	v_bitop3_b32 v231, v23, s13, v4 bitop3:0xde
	v_lshlrev_b32_e32 v4, 2, v188
	v_lshl_add_u64 v[6:7], s[14:15], 0, v[4:5]
	s_mov_b64 s[16:17], 0x200000
	s_cmpk_lt_u32 s12, 0x100
	v_lshl_add_u64 v[190:191], v[6:7], 0, s[16:17]
	s_mov_b64 s[16:17], 0x600000
	s_cselect_b64 s[12:13], -1, 0
	v_lshl_add_u64 v[192:193], v[6:7], 0, s[16:17]
	s_lshl_b32 s16, s18, 10
	s_add_u32 s14, s14, s16
	s_addc_u32 s15, s15, 0
	v_mov_b32_e32 v23, v5
	v_lshl_add_u64 v[6:7], s[14:15], 0, v[22:23]
	v_mov_b32_e32 v21, v5
	v_lshlrev_b32_e32 v4, 15, v14
	v_lshl_add_u64 v[6:7], v[6:7], 0, v[20:21]
	s_mov_b64 s[14:15], 0x5000000
	v_and_b32_e32 v4, 0xffff0000, v4
	v_lshl_add_u64 v[194:195], v[6:7], 0, s[14:15]
	v_lshl_add_u32 v4, v15, 12, v4
	v_and_b32_e32 v6, 1, v14
	v_lshl_or_b32 v4, v6, 6, v4
	v_lshl_add_u32 v196, v16, 1, v4
	v_lshlrev_b32_e32 v4, 15, v17
	v_and_b32_e32 v4, 0xffff0000, v4
	s_waitcnt vmcnt(6)
	v_lshl_add_u32 v4, v18, 12, v4
	v_and_b32_e32 v6, 1, v17
	v_lshl_or_b32 v4, v6, 6, v4
	v_mov_b32_e32 v197, v5
	v_lshl_add_u32 v212, v19, 1, v4
	v_mov_b32_e32 v213, v5
	s_mov_b32 s54, 0
	v_add_u32_e32 v235, 0, v24
	s_barrier
	s_branch .LBB0_652
	s_nop 0
	s_nop 0
	s_nop 0
	s_nop 0
	s_nop 0
	s_nop 0
	s_nop 0
	s_nop 0
	s_nop 0
	s_nop 0
	s_nop 0
	s_nop 0
.LBB0_650:
	s_mov_b64 s[22:23], 0

; #define PG8_STAGE(bufoff, gbase, voff) do { _Pragma("unroll") for (int _i = 0; _i < 2; ++_i) \
;         __builtin_amdgcn_global_load_lds((const unsigned*)((const char*)(gbase) + (voff)[_i]), (LAS unsigned*)(lds + (bufoff) + ldsw + _i * 8192), 16, 0, 0); } while (0)
; #define PG8_BAR __builtin_amdgcn_s_barrier()
; template <class Epi, class Sched>
; __device__ __forceinline__ void gemm_phase(LAS unsigned char* lds, const Gemm g, const Sched& S, const Epi& E) {
;     ...
;     for (int i = 0; i < 2; ++i) { int R, C; stage_rc(tid * 16 + i * 8192, R, C); const int Rb = Epi::PERM ? ((R & ~31) + perm32(R & 31)) : R;
;         voffA[i] = (unsigned)(R * g.lda + C) * 2u; voffB[i] = (unsigned)(Rb * g.ldb + C) * 2u; }
;     const size_t kstep = (size_t)(BK * 2);
;     const size_t hstepA = (size_t)HALF * g.lda * 2, hstepB = (size_t)HALF * g.ldb * 2;
;     const size_t tstepA = 2 * hstepA, tstepB = 2 * hstepB;
;     const unsigned ldsw = (unsigned)wid * 1024u;
;     const int aoff = lds_byte(wr * 64 + fr, fq * 8), boff = lds_byte(wc * 32 + fr, fq * 8);
;     ...
;     Unit cur, nxt; int ui = 0;
;     if (!S.next(0, cur)) return;
;     f32x4 acc[2][2][4][2];
; #pragma unroll
;     for (int a = 0; a < 2; ++a)
; #pragma unroll
;         for (int b = 0; b < 2; ++b)
; #pragma unroll
;             for (int m = 0; m < 4; ++m)
; #pragma unroll
;                 for (int n = 0; n < 2; ++n) acc[a][b][m][n] = (f32x4){0.f, 0.f, 0.f, 0.f};
;     bf16x8 At[4][2], B0[2][2], B1[2][2];
;     const char* cA = (const char*)g.A + (size_t)cur.pm * tstepA + (size_t)cur.ka * 2; const char* cB = (const char*)g.Bt + (size_t)cur.pn * tstepB;
;     S.a_ready(cur);
;     PG8_STAGE(PG8_SB(0, 0), cB, voffB); PG8_STAGE(PG8_SB(0, 1), cB + hstepB, voffB); PG8_STAGE(PG8_SA(0, 0), cA, voffA); PG8_STAGE(PG8_SA(0, 1), cA + hstepA, voffA);
;     if (wr == 1) PG8_BAR;
.LBB0_992:
	v_readlane_b32 s4, v253, 41
	v_mov_b32_e32 v169, v0
	v_readlane_b32 s5, v253, 42
	s_andn2_b64 vcc, exec, s[4:5]
	v_readfirstlane_b32 s51, v169
	s_cbranch_vccnz .LBB0_1073
	s_waitcnt vmcnt(0)
	v_lshlrev_b32_e32 v7, 4, v169
	v_add_u32_e32 v3, 0x2000, v7
	v_ashrrev_i32_e32 v2, 31, v3
	v_lshrrev_b32_e32 v2, 22, v2
	v_add_u32_e32 v2, v3, v2
	v_ashrrev_i32_e32 v4, 10, v2
	v_mul_i32_i24_e32 v6, 0x400, v4
	v_sub_u32_e32 v3, v3, v6
	v_lshrrev_b32_e32 v6, 4, v3
	v_bitop3_b32 v3, v6, v3, 32 bitop3:0x6c
	v_ashrrev_i32_e32 v6, 31, v3
	v_lshrrev_b32_e32 v6, 26, v6
	v_add_u32_e32 v6, v3, v6
	v_ashrrev_i32_e32 v8, 6, v6
	v_and_b32_e32 v6, 0xc0, v6
	v_lshlrev_b32_e32 v2, 5, v4
	v_sub_u32_e32 v3, v3, v6
	v_lshlrev_b32_e32 v4, 3, v4
	v_ashrrev_i16_sdwa v3, v232, sext(v3) dst_sel:DWORD dst_unused:UNUSED_PAD src0_sel:DWORD src1_sel:BYTE_0
	v_and_b32_e32 v4, -16, v4
	v_and_b32_e32 v2, 32, v2
	v_bfe_i32 v3, v3, 0, 16
	v_add_u32_e32 v4, v8, v4
	v_add_u32_e32 v9, v2, v3
	v_mul_lo_u32 v6, v4, s6
	v_add_lshl_u32 v134, v9, v6, 1
	v_mul_lo_u32 v6, v4, s22
	v_add_lshl_u32 v136, v9, v6, 1
	v_bfe_i32 v9, v169, 27, 1
	v_lshrrev_b32_e32 v9, 22, v9
	v_add_u32_e32 v9, v7, v9
	v_and_b32_e32 v9, 0xfffffc00, v9
	v_sub_u32_e32 v7, v7, v9
	v_readlane_b32 s4, v254, 14
	v_ashrrev_i32_e32 v4, 31, v169
	v_lshrrev_b32_e32 v9, 4, v7
	s_mul_i32 s4, s4, s7
	s_lshl_b32 s34, s22, 8
	v_lshrrev_b32_e32 v4, 26, v4
	v_bitop3_b32 v7, v9, v7, 32 bitop3:0x6c
	s_ashr_i32 s5, s4, 31
	s_lshl_b64 s[20:21], s[34:35], 1
	v_add_u32_e32 v4, v169, v4
	v_ashrrev_i32_e32 v9, 31, v7
	s_lshl_b64 s[26:27], s[4:5], 1
	v_readlane_b32 s4, v253, 62
	v_readlane_b32 s23, v253, 61
	v_ashrrev_i32_e32 v8, 6, v4
	v_lshrrev_b32_e32 v9, 26, v9
	s_mul_i32 s4, s20, s4
	s_mul_hi_u32 s5, s20, s23
	v_lshlrev_b32_e32 v4, 5, v8
	v_add_u32_e32 v9, v7, v9
	v_lshlrev_b32_e32 v8, 3, v8
	s_add_i32 s4, s5, s4
	s_bfe_u32 s5, s22, 0x10017
	s_ashr_i32 s50, s51, 6
	v_ashrrev_i32_e32 v10, 6, v9
	v_and_b32_e32 v8, -16, v8
	s_mul_i32 s5, s5, s23
	s_ashr_i32 s52, s51, 8
	s_lshl_b32 s55, s6, 8
	s_lshl_b32 s56, s6, 9
	s_lshl_b32 s57, s50, 10
	v_add_u32_e32 v8, v10, v8
	s_add_i32 s4, s4, s5
	s_mul_i32 s5, s20, s23
	v_mul_lo_u32 v10, v8, s6
	v_mul_lo_u32 v8, v8, s22
	s_add_u32 s22, s12, s5
	v_and_b32_e32 v9, 0xc0, v9
	s_addc_u32 s23, s13, s4
	v_readlane_b32 s4, v253, 63
	v_readlane_b32 s24, v254, 13
	v_sub_u32_e32 v7, v7, v9
	s_mul_i32 s4, s56, s4
	s_mul_hi_u32 s5, s56, s24
	v_ashrrev_i16_sdwa v7, v232, sext(v7) dst_sel:DWORD dst_unused:UNUSED_PAD src0_sel:DWORD src1_sel:BYTE_0
	s_add_i32 s5, s5, s4
	s_mul_i32 s4, s56, s24
	v_and_b32_e32 v4, 32, v4
	v_bfe_i32 v7, v7, 0, 16
	s_add_u32 s24, s16, s4
	v_add_u32_e32 v9, v4, v7
	s_addc_u32 s25, s17, s5
	s_add_i32 s58, s57, 0
	v_add_lshl_u32 v138, v9, v10, 1
	s_add_i32 m0, s58, 0x10000
	v_add_lshl_u32 v140, v9, v8, 1
	global_load_lds_dwordx4 v138, s[24:25]
	s_add_i32 m0, s58, 0x12000
	s_add_u32 s4, s24, s55
	global_load_lds_dwordx4 v134, s[24:25]
	s_addc_u32 s5, s25, 0
	s_add_i32 m0, s58, 0x14000
	s_nop 0
	global_load_lds_dwordx4 v138, s[4:5]
	s_add_i32 m0, s58, 0x16000
	s_add_u32 s26, s22, s26
	s_addc_u32 s27, s23, s27
	s_add_i32 s59, s58, 0x2000
	global_load_lds_dwordx4 v134, s[4:5]
	s_mov_b32 m0, s58
	s_add_u32 s22, s26, s34
	global_load_lds_dwordx4 v140, s[26:27]
	s_mov_b32 m0, s59
	s_addc_u32 s23, s27, 0
	s_add_i32 s60, s58, 0x4000
	global_load_lds_dwordx4 v136, s[26:27]
	s_mov_b32 m0, s60
	s_add_i32 s61, s58, 0x6000
	global_load_lds_dwordx4 v140, s[22:23]
	s_mov_b32 m0, s61
	s_cmp_eq_u32 s52, 1
	global_load_lds_dwordx4 v136, s[22:23]
	s_cselect_b64 s[22:23], -1, 0
	s_cmp_lg_u32 s52, 1
	s_cbranch_scc1 .Lmy_p0_4
	s_barrier
	s_branch .LBB0_995

; #define PG8_STAGE(bufoff, gbase, voff) do { _Pragma("unroll") for (int _i = 0; _i < 2; ++_i) \
;         __builtin_amdgcn_global_load_lds((const unsigned*)((const char*)(gbase) + (voff)[_i]), (LAS unsigned*)(lds + (bufoff) + ldsw + _i * 8192), 16, 0, 0); } while (0)
; #define PG8_WAIT_V(n) asm volatile("s_waitcnt vmcnt(" #n ")" ::: "memory")
; #define PG8_BAR __builtin_amdgcn_s_barrier()
; template <class Epi, class Sched>
; __device__ __forceinline__ void gemm_phase(LAS unsigned char* lds, const Gemm g, const Sched& S, const Epi& E) {
;     ...
;     PG8_STAGE(PG8_SB(0, 0), cB, voffB); PG8_STAGE(PG8_SB(0, 1), cB + hstepB, voffB); PG8_STAGE(PG8_SA(0, 0), cA, voffA); PG8_STAGE(PG8_SA(0, 1), cA + hstepA, voffA);
;     if (wr == 1) PG8_BAR;
;     PG8_WAIT_V(2); PG8_BAR;
;     PG8_STAGE(PG8_SB(1, 0), cB + kstep, voffB); PG8_STAGE(PG8_SA(1, 0), cA + kstep, voffA); PG8_STAGE(PG8_SB(1, 1), cB + hstepB + kstep, voffB);
;     PG8_WAIT_V(6); PG8_BAR;
;     for (;;) {
;     ...
; #pragma unroll
;         for (int a = 0; a < 2; ++a)
; #pragma unroll
;             for (int b = 0; b < 2; ++b)
; #pragma unroll
;                 for (int m = 0; m < 4; ++m)
; #pragma unroll
;                     for (int n = 0; n < 2; ++n) acc[a][b][m][n] = (f32x4){0.f, 0.f, 0.f, 0.f};
;         cur = nxt; cA = nA; cB = nB; ++ui;
.LBB0_995:
	v_mov_b32_e32 v139, v5
	v_lshl_add_u64 v[10:11], s[24:25], 0, v[138:139]
	v_mov_b32_e32 v135, v5
	v_lshl_add_u64 v[12:13], s[24:25], 0, v[134:135]
	v_mov_b32_e32 v141, v5
	s_add_i32 m0, s58, 0x18000
	v_lshl_add_u64 v[10:11], v[10:11], 0, s[36:37]
	v_lshl_add_u64 v[18:19], s[26:27], 0, v[140:141]
	v_mov_b32_e32 v137, v5
	s_waitcnt vmcnt(2)
	s_barrier
	global_load_lds_dwordx4 v[10:11], off
	v_lshl_add_u64 v[10:11], v[12:13], 0, s[36:37]
	s_add_i32 m0, s58, 0x1a000
	s_add_i32 s62, s58, 0x8000
	v_lshl_add_u64 v[20:21], s[26:27], 0, v[136:137]
	global_load_lds_dwordx4 v[10:11], off
	v_lshl_add_u64 v[10:11], v[18:19], 0, s[36:37]
	s_mov_b32 m0, s62
	s_add_i32 s63, s58, 0xa000
	v_lshl_add_u64 v[14:15], s[4:5], 0, v[138:139]
	global_load_lds_dwordx4 v[10:11], off
	v_lshl_add_u64 v[10:11], v[20:21], 0, s[36:37]
	s_mov_b32 m0, s63
	v_lshl_add_u64 v[16:17], s[4:5], 0, v[134:135]
	global_load_lds_dwordx4 v[10:11], off
	s_add_i32 m0, s58, 0x1c000
	v_lshl_add_u64 v[10:11], v[14:15], 0, s[36:37]
	global_load_lds_dwordx4 v[10:11], off
	v_lshl_add_u64 v[10:11], v[16:17], 0, s[36:37]
	s_add_i32 m0, s58, 0x1e000
	v_and_b32_e32 v168, 15, v169
	global_load_lds_dwordx4 v[10:11], off
	v_and_b32_e32 v9, 48, v169
	v_lshlrev_b32_e32 v10, 2, v169
	s_and_b32 s54, s50, 3
	s_lshr_b32 s64, s6, 6
	v_lshl_or_b32 v9, v168, 6, v9
	s_lshl_b32 s4, s52, 13
	v_and_b32_e32 v10, 32, v10
	v_bitop3_b32 v11, v9, s4, v10 bitop3:0xde
	s_lshl_b32 s4, s54, 12
	s_add_i32 s65, s64, -2
	s_cmpk_lt_u32 s51, 0x100
	v_bitop3_b32 v148, v9, s4, v10 bitop3:0xde
	s_cselect_b64 s[28:29], -1, 0
	s_add_u32 s4, s34, 0x80
	v_add_u32_e32 v4, v8, v4
	s_addc_u32 s5, 0, 0
	v_add_lshl_u32 v4, v4, v7, 1
	v_add_u32_e32 v2, v6, v2
	v_lshl_add_u64 v[142:143], s[4:5], 0, v[4:5]
	v_add_lshl_u32 v4, v2, v3, 1
	s_waitcnt vmcnt(6)
	v_lshl_add_u64 v[144:145], s[4:5], 0, v[4:5]
	v_mov_b32_e32 v4, v5
	v_mov_b32_e32 v2, v5
	v_mov_b32_e32 v3, v5
	v_add_u32_e32 v149, 0, v11
	v_mov_b64_e32 v[8:9], v[4:5]
	v_mov_b64_e32 v[12:13], v[4:5]
	v_mov_b64_e32 v[16:17], v[4:5]
	v_mov_b64_e32 v[20:21], v[4:5]
	v_mov_b64_e32 v[24:25], v[4:5]
	v_mov_b64_e32 v[32:33], v[4:5]
	v_mov_b64_e32 v[40:41], v[4:5]
	v_mov_b64_e32 v[48:49], v[4:5]
	v_mov_b64_e32 v[28:29], v[4:5]
	v_mov_b64_e32 v[36:37], v[4:5]
	v_mov_b64_e32 v[44:45], v[4:5]
	v_mov_b64_e32 v[52:53], v[4:5]
	v_mov_b64_e32 v[56:57], v[4:5]
	v_mov_b64_e32 v[60:61], v[4:5]
	v_mov_b64_e32 v[64:65], v[4:5]
	v_mov_b64_e32 v[68:69], v[4:5]
	v_mov_b64_e32 v[72:73], v[4:5]
	v_mov_b64_e32 v[76:77], v[4:5]
	v_mov_b64_e32 v[80:81], v[4:5]
	v_mov_b64_e32 v[84:85], v[4:5]
	v_mov_b64_e32 v[88:89], v[4:5]
	v_mov_b64_e32 v[96:97], v[4:5]
	v_mov_b64_e32 v[104:105], v[4:5]
	v_mov_b64_e32 v[116:117], v[4:5]
	v_mov_b64_e32 v[92:93], v[4:5]
	v_mov_b64_e32 v[100:101], v[4:5]
	v_mov_b64_e32 v[108:109], v[4:5]
	v_mov_b64_e32 v[112:113], v[4:5]
	v_mov_b64_e32 v[120:121], v[4:5]
	v_mov_b64_e32 v[124:125], v[4:5]
	v_mov_b64_e32 v[128:129], v[4:5]
	v_mov_b64_e32 v[132:133], v[4:5]
	v_readlane_b32 s4, v254, 13
	s_mov_b32 s66, 0
	v_mov_b64_e32 v[6:7], v[2:3]
	v_mov_b64_e32 v[10:11], v[2:3]
	v_mov_b64_e32 v[14:15], v[2:3]
	v_mov_b64_e32 v[18:19], v[2:3]
	v_mov_b64_e32 v[22:23], v[2:3]
	v_mov_b64_e32 v[30:31], v[2:3]
	v_mov_b64_e32 v[38:39], v[2:3]
	v_mov_b64_e32 v[46:47], v[2:3]
	v_mov_b64_e32 v[26:27], v[2:3]
	v_mov_b64_e32 v[34:35], v[2:3]
	v_mov_b64_e32 v[42:43], v[2:3]
	v_mov_b64_e32 v[50:51], v[2:3]
	v_mov_b64_e32 v[54:55], v[2:3]
	v_mov_b64_e32 v[58:59], v[2:3]
	v_mov_b64_e32 v[62:63], v[2:3]
	v_mov_b64_e32 v[66:67], v[2:3]
	v_mov_b64_e32 v[70:71], v[2:3]
	v_mov_b64_e32 v[74:75], v[2:3]
	v_mov_b64_e32 v[78:79], v[2:3]
	v_mov_b64_e32 v[82:83], v[2:3]
	v_mov_b64_e32 v[86:87], v[2:3]
	v_mov_b64_e32 v[94:95], v[2:3]
	v_mov_b64_e32 v[102:103], v[2:3]
	v_mov_b64_e32 v[114:115], v[2:3]
	v_mov_b64_e32 v[90:91], v[2:3]
	v_mov_b64_e32 v[98:99], v[2:3]
	v_mov_b64_e32 v[106:107], v[2:3]
	v_mov_b64_e32 v[110:111], v[2:3]
	v_mov_b64_e32 v[118:119], v[2:3]
	v_mov_b64_e32 v[122:123], v[2:3]
	v_mov_b64_e32 v[126:127], v[2:3]
	v_mov_b64_e32 v[130:131], v[2:3]
	s_mov_b32 s6, s4
	v_readlane_b32 s53, v253, 61
	s_barrier
	s_branch .LBB0_998
	s_nop 0
	s_nop 0
	s_nop 0
	s_nop 0
	s_nop 0
	s_nop 0
	s_nop 0
	s_nop 0
	s_nop 0
	s_nop 0
.LBB0_996:
	v_mov_b32_e32 v4, v5
	v_mov_b32_e32 v2, v5
	v_mov_b32_e32 v3, v5
	v_mov_b64_e32 v[8:9], v[4:5]
	v_mov_b64_e32 v[12:13], v[4:5]
	v_mov_b64_e32 v[16:17], v[4:5]
	v_mov_b64_e32 v[20:21], v[4:5]
	v_mov_b64_e32 v[24:25], v[4:5]
	v_mov_b64_e32 v[32:33], v[4:5]
	v_mov_b64_e32 v[40:41], v[4:5]
	v_mov_b64_e32 v[48:49], v[4:5]
	v_mov_b64_e32 v[28:29], v[4:5]
	v_mov_b64_e32 v[36:37], v[4:5]
	v_mov_b64_e32 v[44:45], v[4:5]
	v_mov_b64_e32 v[52:53], v[4:5]
	v_mov_b64_e32 v[56:57], v[4:5]
	v_mov_b64_e32 v[60:61], v[4:5]
	v_mov_b64_e32 v[64:65], v[4:5]
	v_mov_b64_e32 v[68:69], v[4:5]
	v_mov_b64_e32 v[72:73], v[4:5]
	v_mov_b64_e32 v[76:77], v[4:5]
	v_mov_b64_e32 v[80:81], v[4:5]
	v_mov_b64_e32 v[84:85], v[4:5]
	v_mov_b64_e32 v[88:89], v[4:5]
	v_mov_b64_e32 v[96:97], v[4:5]
	v_mov_b64_e32 v[104:105], v[4:5]
	v_mov_b64_e32 v[116:117], v[4:5]
	v_mov_b64_e32 v[92:93], v[4:5]
	v_mov_b64_e32 v[100:101], v[4:5]
	v_mov_b64_e32 v[108:109], v[4:5]
	v_mov_b64_e32 v[112:113], v[4:5]
	v_mov_b64_e32 v[120:121], v[4:5]
	v_mov_b64_e32 v[124:125], v[4:5]
	v_mov_b64_e32 v[128:129], v[4:5]
	v_mov_b64_e32 v[132:133], v[4:5]
	v_mov_b64_e32 v[6:7], v[2:3]
	v_mov_b64_e32 v[10:11], v[2:3]
	v_mov_b64_e32 v[14:15], v[2:3]
	v_mov_b64_e32 v[18:19], v[2:3]
	v_mov_b64_e32 v[22:23], v[2:3]
	v_mov_b64_e32 v[30:31], v[2:3]
	v_mov_b64_e32 v[38:39], v[2:3]
	v_mov_b64_e32 v[46:47], v[2:3]
	v_mov_b64_e32 v[26:27], v[2:3]
	v_mov_b64_e32 v[34:35], v[2:3]
	v_mov_b64_e32 v[42:43], v[2:3]
	v_mov_b64_e32 v[50:51], v[2:3]
	v_mov_b64_e32 v[54:55], v[2:3]
	v_mov_b64_e32 v[58:59], v[2:3]
	v_mov_b64_e32 v[62:63], v[2:3]
	v_mov_b64_e32 v[66:67], v[2:3]
	v_mov_b64_e32 v[70:71], v[2:3]
	v_mov_b64_e32 v[74:75], v[2:3]
	v_mov_b64_e32 v[78:79], v[2:3]
	v_mov_b64_e32 v[82:83], v[2:3]
	v_mov_b64_e32 v[86:87], v[2:3]
	v_mov_b64_e32 v[94:95], v[2:3]
	v_mov_b64_e32 v[102:103], v[2:3]
	v_mov_b64_e32 v[114:115], v[2:3]
	v_mov_b64_e32 v[90:91], v[2:3]
	v_mov_b64_e32 v[98:99], v[2:3]
	v_mov_b64_e32 v[106:107], v[2:3]
	v_mov_b64_e32 v[110:111], v[2:3]
	v_mov_b64_e32 v[118:119], v[2:3]
	v_mov_b64_e32 v[122:123], v[2:3]
	v_mov_b64_e32 v[126:127], v[2:3]
	v_mov_b64_e32 v[130:131], v[2:3]
	s_mov_b32 s6, s67
	s_mov_b32 s53, s68
	s_mov_b64 s[24:25], s[44:45]
	s_mov_b64 s[26:27], s[4:5]
	s_mov_b32 s66, s69
